# phase-0 weight conversion: next tile's loads issued before the current tile is staged to LDS (arrived tile copied to spare registers), all seven large convT loops
# speedup vs baseline: 1.0412x; 1.0081x over previous
.LBB0_1026:
	v_mov_b32_e32 v4, v196
	s_mov_b32 s0, s2
	v_mov_b32_e32 v0, v196
	s_lshl_b32 s0, s0, 1
	v_readfirstlane_b32 s1, v0
	s_ashr_i32 s1, s1, 8
	v_mov_b32_e32 v0, v196
	s_add_i32 s1, s1, s0
	s_nop 0
	v_readfirstlane_b32 s0, v0
	s_ashr_i32 s0, s0, 8
	s_sub_i32 s22, s1, s0
	s_cmpk_gt_i32 s22, 0x33f
	s_cbranch_scc1 .LBB0_1031
	v_readlane_b32 s4, v253, 14
	s_mul_i32 s0, s40, 0x680000
	v_readlane_b32 s6, v253, 16
	v_readlane_b32 s5, v253, 15
	v_readlane_b32 s7, v253, 17
	v_readlane_b32 s8, v253, 18
	v_readlane_b32 s9, v253, 19
	v_readlane_b32 s10, v253, 20
	v_readlane_b32 s11, v253, 21
	v_readlane_b32 s12, v253, 22
	v_readlane_b32 s13, v253, 23
	v_readlane_b32 s14, v253, 24
	v_readlane_b32 s15, v253, 25
	v_readlane_b32 s16, v253, 26
	v_readlane_b32 s17, v253, 27
	v_readlane_b32 s18, v253, 28
	v_readlane_b32 s19, v253, 29
	s_add_u32 s0, s6, s0
	s_addc_u32 s1, s7, 0
	v_readlane_b32 s4, v254, 59
	s_mul_i32 s20, s40, 0xd00000
	v_readlane_b32 s8, v254, 63
	v_mov_b32_e32 v0, v196
	v_readlane_b32 s9, v255, 0
	s_add_u32 s20, s8, s20
	s_addc_u32 s21, s9, 0
	v_readfirstlane_b32 s23, v0
	s_ashr_i32 s23, s23, 8
	s_add_i32 s23, s23, s22
	s_min_i32 s23, s23, 0x33f
	s_ashr_i32 s26, s23, 31
	s_lshr_b32 s26, s26, 28
	s_add_i32 s26, s23, s26
	s_and_b32 s27, s26, 0x3fff0
	v_bfe_u32 v6, v4, 6, 2
	s_sub_i32 s23, s23, s27
	v_lshl_or_b32 v5, s23, 6, v6
	s_lshl_b32 s23, s26, 2
	s_and_b32 s26, s23, 0xffffffc0
	s_ashr_i32 s27, s26, 31
	s_lshl_b64 s[26:27], s[26:27], 2
	s_add_u32 s26, s20, s26
	v_lshlrev_b32_e32 v0, 2, v4
	s_addc_u32 s27, s21, s27
	v_and_b32_e32 v0, 0xfc, v0
	s_waitcnt vmcnt(1)
	v_mul_lo_u32 v8, v5, s50
	v_lshl_add_u64 v[2:3], s[26:27], 0, v[0:1]
	v_ashrrev_i32_e32 v9, 31, v8
	v_lshl_add_u64 v[2:3], v[8:9], 2, v[2:3]
	v_add_co_u32_e32 v8, vcc, s48, v2
	s_mov_b32 s4, 0x27000
	s_nop 0
	v_addc_co_u32_e32 v9, vcc, 0, v3, vcc
	v_add_co_u32_e32 v10, vcc, s55, v2
	s_mov_b32 s23, 0xa9000
	s_nop 0
	v_addc_co_u32_e32 v11, vcc, 0, v3, vcc
	v_add_co_u32_e32 v12, vcc, s4, v2
	s_mov_b32 s4, 0x34000
	s_nop 0
	v_addc_co_u32_e32 v13, vcc, 0, v3, vcc
	v_add_co_u32_e32 v14, vcc, s4, v2
	s_mov_b32 s4, 0x41000
	s_nop 0
	v_addc_co_u32_e32 v15, vcc, 0, v3, vcc
	s_waitcnt vmcnt(0)
	v_add_co_u32_e32 v16, vcc, s4, v2
	s_mov_b32 s4, 0x5b000
	s_nop 0
	v_addc_co_u32_e32 v17, vcc, 0, v3, vcc
	v_add_co_u32_e32 v20, vcc, s53, v2
	v_mov_b32_e32 v5, v1
	s_nop 0
	v_addc_co_u32_e32 v21, vcc, 0, v3, vcc
	v_add_co_u32_e32 v22, vcc, s4, v2
	s_mov_b32 s4, 0x68000
	s_waitcnt lgkmcnt(4)
	v_addc_co_u32_e32 v23, vcc, 0, v3, vcc
	global_load_dword v7, v[2:3], off nt
	s_nop 0
	global_load_dword v9, v[8:9], off nt
	s_nop 0
	global_load_dword v10, v[10:11], off nt
	s_nop 0
	global_load_dword v11, v[12:13], off nt
	s_nop 0
	global_load_dword v12, v[14:15], off nt
	s_nop 0
	global_load_dword v14, v[16:17], off nt
	s_nop 0
	global_load_dword v16, v[20:21], off nt
	global_load_dword v17, v[22:23], off nt
	v_add_co_u32_e32 v20, vcc, s4, v2
	s_mov_b32 s4, 0x75000
	s_nop 0
	v_addc_co_u32_e32 v21, vcc, 0, v3, vcc
	v_add_co_u32_e32 v22, vcc, s4, v2
	s_mov_b32 s4, 0x82000
	s_nop 0
	v_addc_co_u32_e32 v23, vcc, 0, v3, vcc
	v_add_co_u32_e32 v24, vcc, s4, v2
	s_mov_b32 s4, 0x8f000
	s_nop 0
	v_addc_co_u32_e32 v25, vcc, 0, v3, vcc
	v_add_co_u32_e32 v26, vcc, s4, v2
	s_mov_b32 s4, 0x9c000
	s_nop 0
	v_addc_co_u32_e32 v27, vcc, 0, v3, vcc
	v_add_co_u32_e32 v28, vcc, s4, v2
	v_bfe_u32 v8, v4, 3, 5
	s_nop 0
	v_addc_co_u32_e32 v29, vcc, 0, v3, vcc
	v_add_co_u32_e32 v30, vcc, s23, v2
	s_mov_b32 s23, 0xb6000
	s_nop 0
	v_addc_co_u32_e32 v31, vcc, 0, v3, vcc
	s_waitcnt lgkmcnt(0)
	v_add_co_u32_e32 v32, vcc, s23, v2
	s_mov_b32 s23, 0xc3000
	s_nop 0
	v_addc_co_u32_e32 v33, vcc, 0, v3, vcc
	v_add_co_u32_e32 v2, vcc, s23, v2
	v_lshlrev_b32_e32 v4, 3, v4
	s_nop 0
	v_addc_co_u32_e32 v3, vcc, 0, v3, vcc
	global_load_dword v19, v[20:21], off nt
	s_nop 0
	global_load_dword v20, v[22:23], off nt
	global_load_dword v21, v[24:25], off nt
	s_nop 0
	global_load_dword v22, v[26:27], off nt
	global_load_dword v23, v[28:29], off nt
	global_load_dword v24, v[30:31], off nt
	global_load_dword v25, v[32:33], off nt
	s_nop 0
	global_load_dword v26, v[2:3], off nt
	v_and_b32_e32 v13, 56, v4
	v_mul_u32_u24_e32 v15, 0x41, v13
	v_lshlrev_b32_e32 v15, 2, v15
	v_lshlrev_b32_e32 v27, 2, v8
	v_lshlrev_b32_e32 v4, 1, v13
	v_add3_u32 v15, s33, v15, v27
	v_mul_u32_u24_e32 v27, 0x104, v6
	v_lshl_add_u64 v[2:3], s[20:21], 0, v[0:1]
	v_lshl_add_u64 v[4:5], s[0:1], 0, v[4:5]
	v_or_b32_e32 v13, 32, v8
	v_add3_u32 v0, s33, v27, v0
	v_readlane_b32 s5, v254, 60
	v_readlane_b32 s6, v254, 61
	v_readlane_b32 s7, v254, 62
	v_readlane_b32 s10, v255, 1
	v_readlane_b32 s11, v255, 2
	v_readlane_b32 s12, v255, 3
	v_readlane_b32 s13, v255, 4
	v_readlane_b32 s14, v255, 5
	v_readlane_b32 s15, v255, 6
	v_readlane_b32 s16, v255, 7
	v_readlane_b32 s17, v255, 8
	v_readlane_b32 s18, v255, 9
	v_readlane_b32 s19, v255, 10
	s_waitcnt vmcnt(0)
	s_branch .LBB0_1029

.LBB0_1029:
	v_mov_b32_e32 v27, v196
	s_mov_b32 s0, s34
	s_waitcnt vmcnt(2)
	v_mov_b32_e32 v80, v7
	v_mov_b32_e32 v81, v9
	v_mov_b32_e32 v82, v10
	v_mov_b32_e32 v83, v11
	v_mov_b32_e32 v84, v12
	v_mov_b32_e32 v85, v14
	v_mov_b32_e32 v86, v16
	v_mov_b32_e32 v87, v17
	v_mov_b32_e32 v88, v19
	v_mov_b32_e32 v89, v20
	v_mov_b32_e32 v90, v21
	v_mov_b32_e32 v91, v22
	v_mov_b32_e32 v92, v23
	v_mov_b32_e32 v93, v24
	v_mov_b32_e32 v94, v25
	v_mov_b32_e32 v95, v26
	s_lshl_b32 s0, s0, 1
	s_add_i32 s0, s0, s22
	s_cmpk_gt_i32 s0, 0x33f
	v_readfirstlane_b32 s0, v27
	s_cbranch_scc1 .Lcv10_nn
	s_mov_b32 s1, s34
	v_mov_b32_e32 v7, v196
	s_lshl_b32 s1, s1, 1
	s_add_i32 s1, s1, s22
	v_readfirstlane_b32 s20, v7
	s_ashr_i32 s20, s20, 8
	s_add_i32 s1, s1, s20
	s_min_i32 s1, s1, 0x33f
	s_ashr_i32 s20, s1, 31
	s_lshr_b32 s20, s20, 28
	s_add_i32 s20, s1, s20
	s_and_b32 s21, s20, 0x3fff0
	s_sub_i32 s1, s1, s21
	v_lshl_or_b32 v7, s1, 6, v6
	s_lshl_b32 s1, s20, 2
	s_and_b32 s20, s1, 0xffffffc0
	s_ashr_i32 s21, s20, 31
	v_mul_lo_u32 v16, v7, s50
	v_lshl_add_u64 v[10:11], s[20:21], 2, v[2:3]
	v_ashrrev_i32_e32 v17, 31, v16
	v_lshl_add_u64 v[20:21], v[16:17], 2, v[10:11]
	v_add_co_u32_e32 v10, vcc, s48, v20
	s_mov_b32 s1, 0x27000
	s_nop 0
	v_addc_co_u32_e32 v11, vcc, 0, v21, vcc
	v_add_co_u32_e32 v16, vcc, s55, v20
	s_nop 1
	v_addc_co_u32_e32 v17, vcc, 0, v21, vcc
	v_add_co_u32_e32 v22, vcc, s1, v20
	s_mov_b32 s1, 0x34000
	s_nop 0
	v_addc_co_u32_e32 v23, vcc, 0, v21, vcc
	v_add_co_u32_e32 v24, vcc, s1, v20
	s_mov_b32 s1, 0x41000
	s_nop 0
	v_addc_co_u32_e32 v25, vcc, 0, v21, vcc
	v_add_co_u32_e32 v26, vcc, s1, v20
	s_mov_b32 s1, 0x5b000
	s_nop 0
	v_addc_co_u32_e32 v27, vcc, 0, v21, vcc
	v_add_co_u32_e32 v28, vcc, s53, v20
	s_nop 1
	v_addc_co_u32_e32 v29, vcc, 0, v21, vcc
	v_add_co_u32_e32 v30, vcc, s1, v20
	s_mov_b32 s1, 0x68000
	s_nop 0
	v_addc_co_u32_e32 v31, vcc, 0, v21, vcc
	global_load_dword v7, v[20:21], off nt
	global_load_dword v9, v[10:11], off nt
	s_nop 0
	global_load_dword v10, v[16:17], off nt
	global_load_dword v11, v[22:23], off nt
	global_load_dword v12, v[24:25], off nt
	global_load_dword v14, v[26:27], off nt
	s_nop 0
	global_load_dword v16, v[28:29], off nt
	global_load_dword v17, v[30:31], off nt
	v_add_co_u32_e32 v22, vcc, s1, v20
	s_mov_b32 s1, 0x75000
	s_nop 0
	v_addc_co_u32_e32 v23, vcc, 0, v21, vcc
	v_add_co_u32_e32 v24, vcc, s1, v20
	s_mov_b32 s1, 0x82000
	s_nop 0
	v_addc_co_u32_e32 v25, vcc, 0, v21, vcc
	v_add_co_u32_e32 v26, vcc, s1, v20
	s_mov_b32 s1, 0x8f000
	s_nop 0
	v_addc_co_u32_e32 v27, vcc, 0, v21, vcc
	v_add_co_u32_e32 v28, vcc, s1, v20
	s_nop 1
	v_addc_co_u32_e32 v29, vcc, 0, v21, vcc
	v_add_co_u32_e32 v30, vcc, 0x9c000, v20
	s_nop 1
	v_addc_co_u32_e32 v31, vcc, 0, v21, vcc
	v_add_co_u32_e32 v32, vcc, 0xa9000, v20
	s_nop 1
	v_addc_co_u32_e32 v33, vcc, 0, v21, vcc
	v_add_co_u32_e32 v34, vcc, 0xb6000, v20
	s_nop 1
	v_addc_co_u32_e32 v35, vcc, 0, v21, vcc
	v_add_co_u32_e32 v36, vcc, 0xc3000, v20
	s_nop 1
	v_addc_co_u32_e32 v37, vcc, 0, v21, vcc
	global_load_dword v19, v[22:23], off nt
	global_load_dword v20, v[24:25], off nt
	global_load_dword v21, v[26:27], off nt
	s_nop 0
	global_load_dword v22, v[28:29], off nt
	global_load_dword v23, v[30:31], off nt
	global_load_dword v24, v[32:33], off nt
	global_load_dword v25, v[34:35], off nt
	global_load_dword v26, v[36:37], off nt
.Lcv10_nn:
	ds_write_b32 v0, v80
	ds_write_b32 v0, v81 offset:1040
	ds_write_b32 v0, v82 offset:2080
	ds_write_b32 v0, v83 offset:3120
	ds_write_b32 v0, v84 offset:4160
	ds_write_b32 v0, v85 offset:5200
	ds_write_b32 v0, v86 offset:6240
	ds_write_b32 v0, v87 offset:7280
	ds_write_b32 v0, v88 offset:8320
	ds_write_b32 v0, v89 offset:9360
	ds_write_b32 v0, v90 offset:10400
	ds_write_b32 v0, v91 offset:11440
	ds_write_b32 v0, v92 offset:12480
	ds_write_b32 v0, v93 offset:13520
	ds_write_b32 v0, v94 offset:14560
	ds_write_b32 v0, v95 offset:15600
	s_waitcnt lgkmcnt(0)
	s_barrier
	s_branch .LBB0_1028
.LBB0_1031:
	v_mov_b32_e32 v4, v196
	s_mov_b32 s0, s2
	v_mov_b32_e32 v0, v196
	s_lshl_b32 s0, s0, 1
	v_readfirstlane_b32 s1, v0
	s_ashr_i32 s1, s1, 8
	v_mov_b32_e32 v0, v196
	s_add_i32 s1, s1, s0
	s_lshl_b64 s[42:43], s[40:41], 20
	v_readfirstlane_b32 s0, v0
	s_ashr_i32 s0, s0, 8
	s_sub_i32 s22, s1, s0
	s_cmpk_gt_i32 s22, 0xff
	s_cbranch_scc1 .LBB0_1036
	v_readlane_b32 s4, v253, 14
	s_lshl_b64 s[0:1], s[42:43], 1
	v_readlane_b32 s8, v253, 18
	v_readlane_b32 s5, v253, 15
	v_readlane_b32 s6, v253, 16
	v_readlane_b32 s7, v253, 17
	v_readlane_b32 s9, v253, 19
	v_readlane_b32 s10, v253, 20
	v_readlane_b32 s11, v253, 21
	v_readlane_b32 s12, v253, 22
	v_readlane_b32 s13, v253, 23
	v_readlane_b32 s14, v253, 24
	v_readlane_b32 s15, v253, 25
	v_readlane_b32 s16, v253, 26
	v_readlane_b32 s17, v253, 27
	v_readlane_b32 s18, v253, 28
	v_readlane_b32 s19, v253, 29
	s_add_u32 s0, s8, s0
	s_addc_u32 s1, s9, s1
	v_readlane_b32 s4, v254, 59
	s_lshl_b64 s[20:21], s[42:43], 2
	v_readlane_b32 s10, v255, 1
	v_mov_b32_e32 v0, v196
	v_readlane_b32 s11, v255, 2
	s_add_u32 s20, s10, s20
	s_addc_u32 s21, s11, s21
	v_readfirstlane_b32 s23, v0
	s_ashr_i32 s23, s23, 8
	s_add_i32 s23, s23, s22
	s_min_i32 s23, s23, 0xff
	s_ashr_i32 s26, s23, 31
	s_lshr_b32 s26, s26, 28
	s_add_i32 s26, s23, s26
	s_and_b32 s27, s26, 0x3fffff0
	v_bfe_u32 v6, v4, 6, 2
	s_sub_i32 s23, s23, s27
	v_lshl_or_b32 v2, s23, 6, v6
	s_lshl_b32 s23, s26, 2
	s_and_b32 s26, s23, 0xffffffc0
	s_ashr_i32 s27, s26, 31
	s_lshl_b64 s[26:27], s[26:27], 2
	s_add_u32 s26, s20, s26
	v_lshlrev_b32_e32 v0, 2, v4
	s_waitcnt vmcnt(15)
	v_or_b32_e32 v10, 4, v2
	s_waitcnt vmcnt(13)
	v_or_b32_e32 v12, 8, v2
	s_waitcnt vmcnt(12)
	v_or_b32_e32 v14, 12, v2
	s_waitcnt vmcnt(0)
	v_or_b32_e32 v16, 16, v2
	v_or_b32_e32 v22, 20, v2
	v_or_b32_e32 v24, 24, v2
	v_or_b32_e32 v26, 28, v2
	s_addc_u32 s27, s21, s27
	v_and_b32_e32 v0, 0xfc, v0
	v_ashrrev_i32_e32 v3, 31, v2
	v_ashrrev_i32_e32 v11, 31, v10
	v_ashrrev_i32_e32 v13, 31, v12
	v_ashrrev_i32_e32 v15, 31, v14
	v_ashrrev_i32_e32 v17, 31, v16
	s_waitcnt lgkmcnt(4)
	v_ashrrev_i32_e32 v23, 31, v22
	v_ashrrev_i32_e32 v25, 31, v24
	v_ashrrev_i32_e32 v27, 31, v26
	v_lshl_add_u64 v[20:21], s[26:27], 0, v[0:1]
	v_lshlrev_b64 v[8:9], 12, v[2:3]
	v_lshlrev_b64 v[10:11], 12, v[10:11]
	v_lshlrev_b64 v[12:13], 12, v[12:13]
	v_lshlrev_b64 v[14:15], 12, v[14:15]
	v_lshlrev_b64 v[16:17], 12, v[16:17]
	v_lshlrev_b64 v[22:23], 12, v[22:23]
	v_lshlrev_b64 v[24:25], 12, v[24:25]
	v_lshlrev_b64 v[26:27], 12, v[26:27]
	v_lshl_add_u64 v[8:9], v[20:21], 0, v[8:9]
	v_lshl_add_u64 v[10:11], v[20:21], 0, v[10:11]
	v_lshl_add_u64 v[12:13], v[20:21], 0, v[12:13]
	v_lshl_add_u64 v[14:15], v[20:21], 0, v[14:15]
	v_lshl_add_u64 v[16:17], v[20:21], 0, v[16:17]
	v_lshl_add_u64 v[22:23], v[20:21], 0, v[22:23]
	v_lshl_add_u64 v[24:25], v[20:21], 0, v[24:25]
	v_lshl_add_u64 v[26:27], v[20:21], 0, v[26:27]
	global_load_dword v8, v[8:9], off nt
	s_nop 0
	global_load_dword v9, v[10:11], off nt
	s_nop 0
	global_load_dword v11, v[12:13], off nt
	s_nop 0
	global_load_dword v13, v[14:15], off nt
	s_nop 0
	global_load_dword v14, v[16:17], off nt
	global_load_dword v15, v[22:23], off nt
	s_nop 0
	global_load_dword v16, v[24:25], off nt
	global_load_dword v17, v[26:27], off nt
	v_or_b32_e32 v22, 32, v2
	v_or_b32_e32 v24, 36, v2
	v_or_b32_e32 v26, 40, v2
	v_ashrrev_i32_e32 v23, 31, v22
	v_ashrrev_i32_e32 v25, 31, v24
	v_ashrrev_i32_e32 v27, 31, v26
	v_or_b32_e32 v28, 44, v2
	v_or_b32_e32 v30, 48, v2
	s_waitcnt lgkmcnt(0)
	v_or_b32_e32 v32, 52, v2
	v_or_b32_e32 v34, 56, v2
	v_or_b32_e32 v2, 60, v2
	v_lshlrev_b64 v[22:23], 12, v[22:23]
	v_lshlrev_b64 v[24:25], 12, v[24:25]
	v_lshlrev_b64 v[26:27], 12, v[26:27]
	v_ashrrev_i32_e32 v29, 31, v28
	v_ashrrev_i32_e32 v31, 31, v30
	v_ashrrev_i32_e32 v33, 31, v32
	v_ashrrev_i32_e32 v35, 31, v34
	v_ashrrev_i32_e32 v3, 31, v2
	v_lshl_add_u64 v[22:23], v[20:21], 0, v[22:23]
	v_lshl_add_u64 v[24:25], v[20:21], 0, v[24:25]
	v_lshl_add_u64 v[26:27], v[20:21], 0, v[26:27]
	v_lshlrev_b64 v[28:29], 12, v[28:29]
	v_lshlrev_b64 v[30:31], 12, v[30:31]
	v_lshlrev_b64 v[32:33], 12, v[32:33]
	v_lshlrev_b64 v[34:35], 12, v[34:35]
	v_lshlrev_b64 v[2:3], 12, v[2:3]
	v_lshl_add_u64 v[28:29], v[20:21], 0, v[28:29]
	v_lshl_add_u64 v[30:31], v[20:21], 0, v[30:31]
	v_lshl_add_u64 v[32:33], v[20:21], 0, v[32:33]
	v_lshl_add_u64 v[34:35], v[20:21], 0, v[34:35]
	v_lshl_add_u64 v[2:3], v[20:21], 0, v[2:3]
	global_load_dword v19, v[22:23], off nt
	global_load_dword v20, v[24:25], off nt
	global_load_dword v21, v[26:27], off nt
	s_nop 0
	global_load_dword v22, v[28:29], off nt
	global_load_dword v23, v[30:31], off nt
	global_load_dword v24, v[32:33], off nt
	global_load_dword v25, v[34:35], off nt
	global_load_dword v26, v[2:3], off nt
	v_bfe_u32 v7, v4, 3, 5
	v_lshlrev_b32_e32 v4, 3, v4
	v_and_b32_e32 v10, 56, v4
	v_mul_u32_u24_e32 v12, 0x41, v10
	v_lshlrev_b32_e32 v12, 2, v12
	v_lshlrev_b32_e32 v27, 2, v7
	v_lshlrev_b32_e32 v4, 1, v10
	v_mov_b32_e32 v5, v1
	v_add3_u32 v12, s33, v12, v27
	v_mul_u32_u24_e32 v27, 0x104, v6
	v_lshl_add_u64 v[2:3], s[20:21], 0, v[0:1]
	v_lshl_add_u64 v[4:5], s[0:1], 0, v[4:5]
	v_or_b32_e32 v10, 32, v7
	v_add3_u32 v0, s33, v27, v0
	v_readlane_b32 s5, v254, 60
	v_readlane_b32 s6, v254, 61
	v_readlane_b32 s7, v254, 62
	v_readlane_b32 s8, v254, 63
	v_readlane_b32 s9, v255, 0
	v_readlane_b32 s12, v255, 3
	v_readlane_b32 s13, v255, 4
	v_readlane_b32 s14, v255, 5
	v_readlane_b32 s15, v255, 6
	v_readlane_b32 s16, v255, 7
	v_readlane_b32 s17, v255, 8
	v_readlane_b32 s18, v255, 9
	v_readlane_b32 s19, v255, 10
	s_waitcnt vmcnt(0)
	s_branch .LBB0_1034

.LBB0_1034:
	v_mov_b32_e32 v27, v196
	s_mov_b32 s0, s34
	s_waitcnt vmcnt(2)
	v_mov_b32_e32 v80, v8
	v_mov_b32_e32 v81, v9
	v_mov_b32_e32 v82, v11
	v_mov_b32_e32 v83, v13
	v_mov_b32_e32 v84, v14
	v_mov_b32_e32 v85, v15
	v_mov_b32_e32 v86, v16
	v_mov_b32_e32 v87, v17
	v_mov_b32_e32 v88, v19
	v_mov_b32_e32 v89, v20
	v_mov_b32_e32 v90, v21
	v_mov_b32_e32 v91, v22
	v_mov_b32_e32 v92, v23
	v_mov_b32_e32 v93, v24
	v_mov_b32_e32 v94, v25
	v_mov_b32_e32 v95, v26
	s_lshl_b32 s0, s0, 1
	s_add_i32 s0, s0, s22
	s_cmpk_gt_i32 s0, 0xff
	v_readfirstlane_b32 s0, v27
	s_cbranch_scc1 .Lcv11_nn
	s_mov_b32 s1, s34
	v_mov_b32_e32 v8, v196
	s_lshl_b32 s1, s1, 1
	s_add_i32 s1, s1, s22
	v_readfirstlane_b32 s20, v8
	s_ashr_i32 s20, s20, 8
	s_add_i32 s1, s1, s20
	s_min_i32 s1, s1, 0xff
	s_ashr_i32 s20, s1, 31
	s_lshr_b32 s20, s20, 28
	s_add_i32 s20, s1, s20
	s_and_b32 s21, s20, 0x3fffff0
	s_sub_i32 s1, s1, s21
	v_lshl_or_b32 v20, s1, 6, v6
	s_lshl_b32 s1, s20, 2
	s_and_b32 s20, s1, 0xffffffc0
	v_or_b32_e32 v14, 4, v20
	v_or_b32_e32 v16, 8, v20
	v_or_b32_e32 v24, 12, v20
	v_or_b32_e32 v26, 16, v20
	s_ashr_i32 s21, s20, 31
	v_ashrrev_i32_e32 v21, 31, v20
	v_ashrrev_i32_e32 v15, 31, v14
	v_ashrrev_i32_e32 v17, 31, v16
	v_ashrrev_i32_e32 v25, 31, v24
	v_ashrrev_i32_e32 v27, 31, v26
	v_or_b32_e32 v28, 20, v20
	v_or_b32_e32 v30, 24, v20
	v_or_b32_e32 v32, 28, v20
	v_lshl_add_u64 v[22:23], s[20:21], 2, v[2:3]
	v_lshlrev_b64 v[8:9], 12, v[20:21]
	v_lshlrev_b64 v[14:15], 12, v[14:15]
	v_lshlrev_b64 v[16:17], 12, v[16:17]
	v_lshlrev_b64 v[24:25], 12, v[24:25]
	v_lshlrev_b64 v[26:27], 12, v[26:27]
	v_ashrrev_i32_e32 v29, 31, v28
	v_ashrrev_i32_e32 v31, 31, v30
	v_ashrrev_i32_e32 v33, 31, v32
	v_lshl_add_u64 v[8:9], v[22:23], 0, v[8:9]
	v_lshl_add_u64 v[14:15], v[22:23], 0, v[14:15]
	v_lshl_add_u64 v[16:17], v[22:23], 0, v[16:17]
	v_lshl_add_u64 v[24:25], v[22:23], 0, v[24:25]
	v_lshl_add_u64 v[26:27], v[22:23], 0, v[26:27]
	v_lshlrev_b64 v[28:29], 12, v[28:29]
	v_lshlrev_b64 v[30:31], 12, v[30:31]
	v_lshlrev_b64 v[32:33], 12, v[32:33]
	v_lshl_add_u64 v[28:29], v[22:23], 0, v[28:29]
	v_lshl_add_u64 v[30:31], v[22:23], 0, v[30:31]
	v_lshl_add_u64 v[32:33], v[22:23], 0, v[32:33]
	global_load_dword v8, v[8:9], off nt
	s_nop 0
	global_load_dword v9, v[14:15], off nt
	global_load_dword v11, v[16:17], off nt
	global_load_dword v13, v[24:25], off nt
	s_nop 0
	global_load_dword v14, v[26:27], off nt
	global_load_dword v15, v[28:29], off nt
	global_load_dword v16, v[30:31], off nt
	global_load_dword v17, v[32:33], off nt
	v_or_b32_e32 v24, 32, v20
	v_or_b32_e32 v26, 36, v20
	v_ashrrev_i32_e32 v25, 31, v24
	v_ashrrev_i32_e32 v27, 31, v26
	v_or_b32_e32 v28, 40, v20
	v_or_b32_e32 v30, 44, v20
	v_or_b32_e32 v32, 48, v20
	v_or_b32_e32 v34, 52, v20
	v_or_b32_e32 v36, 56, v20
	v_or_b32_e32 v20, 60, v20
	v_lshlrev_b64 v[24:25], 12, v[24:25]
	v_lshlrev_b64 v[26:27], 12, v[26:27]
	v_ashrrev_i32_e32 v29, 31, v28
	v_ashrrev_i32_e32 v31, 31, v30
	v_ashrrev_i32_e32 v33, 31, v32
	v_ashrrev_i32_e32 v35, 31, v34
	v_ashrrev_i32_e32 v37, 31, v36
	v_ashrrev_i32_e32 v21, 31, v20
	v_lshl_add_u64 v[24:25], v[22:23], 0, v[24:25]
	v_lshl_add_u64 v[26:27], v[22:23], 0, v[26:27]
	v_lshlrev_b64 v[28:29], 12, v[28:29]
	v_lshlrev_b64 v[30:31], 12, v[30:31]
	v_lshlrev_b64 v[32:33], 12, v[32:33]
	v_lshlrev_b64 v[34:35], 12, v[34:35]
	v_lshlrev_b64 v[36:37], 12, v[36:37]
	v_lshlrev_b64 v[20:21], 12, v[20:21]
	v_lshl_add_u64 v[28:29], v[22:23], 0, v[28:29]
	v_lshl_add_u64 v[30:31], v[22:23], 0, v[30:31]
	v_lshl_add_u64 v[32:33], v[22:23], 0, v[32:33]
	v_lshl_add_u64 v[34:35], v[22:23], 0, v[34:35]
	v_lshl_add_u64 v[36:37], v[22:23], 0, v[36:37]
	v_lshl_add_u64 v[42:43], v[22:23], 0, v[20:21]
	global_load_dword v19, v[24:25], off nt
	global_load_dword v20, v[26:27], off nt
	global_load_dword v21, v[28:29], off nt
	global_load_dword v22, v[30:31], off nt
	global_load_dword v23, v[32:33], off nt
	s_nop 0
	global_load_dword v24, v[34:35], off nt
	global_load_dword v25, v[36:37], off nt
	global_load_dword v26, v[42:43], off nt

.LBB0_1036:
	v_mov_b32_e32 v4, v196
	s_mov_b32 s0, s2
	v_mov_b32_e32 v0, v196
	s_lshl_b32 s0, s0, 1
	v_readfirstlane_b32 s1, v0
	s_ashr_i32 s1, s1, 8
	v_mov_b32_e32 v0, v196
	s_add_i32 s1, s1, s0
	s_nop 0
	v_readfirstlane_b32 s0, v0
	s_ashr_i32 s0, s0, 8
	s_sub_i32 s22, s1, s0
	s_cmpk_gt_i32 s22, 0x2ff
	s_cbranch_scc1 .LBB0_1041
	v_readlane_b32 s4, v253, 14
	s_mul_i32 s0, s40, 0x600000
	v_readlane_b32 s12, v253, 22
	v_readlane_b32 s13, v253, 23
	s_add_u32 s0, s12, s0
	s_addc_u32 s1, s13, 0
	s_mul_i32 s20, s40, 0xc00000
	v_mov_b32_e32 v0, v196
	s_add_u32 s20, s74, s20
	s_addc_u32 s21, s75, 0
	v_readfirstlane_b32 s23, v0
	s_ashr_i32 s23, s23, 8
	s_add_i32 s23, s23, s22
	s_min_i32 s23, s23, 0x2ff
	s_ashr_i32 s26, s23, 31
	s_lshr_b32 s26, s26, 28
	s_add_i32 s26, s23, s26
	s_and_b32 s27, s26, 0xfff0
	v_bfe_u32 v6, v4, 6, 2
	s_sub_i32 s23, s23, s27
	v_lshl_or_b32 v5, s23, 6, v6
	s_lshl_b32 s23, s26, 2
	s_and_b32 s26, s23, 0xffffffc0
	s_ashr_i32 s27, s26, 31
	s_lshl_b64 s[26:27], s[26:27], 2
	s_add_u32 s26, s20, s26
	v_lshlrev_b32_e32 v0, 2, v4
	s_addc_u32 s27, s21, s27
	v_and_b32_e32 v0, 0xfc, v0
	s_waitcnt vmcnt(1)
	v_mul_lo_u32 v8, v5, s47
	v_lshl_add_u64 v[2:3], s[26:27], 0, v[0:1]
	v_ashrrev_i32_e32 v9, 31, v8
	v_lshl_add_u64 v[2:3], v[8:9], 2, v[2:3]
	v_add_co_u32_e32 v10, vcc, s36, v2
	s_mov_b32 s4, 0x60000
	s_nop 0
	v_addc_co_u32_e32 v11, vcc, 0, v3, vcc
	v_add_co_u32_e32 v12, vcc, s35, v2
	s_mov_b32 s23, 0x6c000
	s_nop 0
	v_addc_co_u32_e32 v13, vcc, 0, v3, vcc
	v_add_co_u32_e32 v14, vcc, s51, v2
	v_bfe_u32 v7, v4, 3, 5
	s_nop 0
	v_addc_co_u32_e32 v15, vcc, 0, v3, vcc
	s_waitcnt vmcnt(0)
	v_add_co_u32_e32 v16, vcc, s52, v2
	v_lshlrev_b32_e32 v4, 3, v4
	s_nop 0
	v_addc_co_u32_e32 v17, vcc, 0, v3, vcc
	v_add_co_u32_e32 v20, vcc, s96, v2
	v_and_b32_e32 v9, 56, v4
	s_nop 0
	v_addc_co_u32_e32 v21, vcc, 0, v3, vcc
	v_add_co_u32_e32 v22, vcc, s46, v2
	v_lshlrev_b32_e32 v4, 1, v9
	s_waitcnt lgkmcnt(4)
	v_addc_co_u32_e32 v23, vcc, 0, v3, vcc
	v_add_co_u32_e32 v24, vcc, s97, v2
	v_mov_b32_e32 v5, v1
	s_nop 0
	v_addc_co_u32_e32 v25, vcc, 0, v3, vcc
	global_load_dword v8, v[2:3], off nt
	s_nop 0
	global_load_dword v10, v[10:11], off nt
	s_nop 0
	global_load_dword v12, v[12:13], off nt
	s_nop 0
	global_load_dword v13, v[14:15], off nt
	s_nop 0
	global_load_dword v14, v[16:17], off nt
	global_load_dword v15, v[20:21], off nt
	s_nop 0
	global_load_dword v16, v[22:23], off nt
	global_load_dword v17, v[24:25], off nt
	v_add_co_u32_e32 v20, vcc, s4, v2
	s_mov_b32 s4, 0x84000
	s_nop 0
	v_addc_co_u32_e32 v21, vcc, 0, v3, vcc
	v_add_co_u32_e32 v22, vcc, s23, v2
	s_mov_b32 s23, 0x78000
	s_nop 0
	v_addc_co_u32_e32 v23, vcc, 0, v3, vcc
	v_add_co_u32_e32 v24, vcc, s23, v2
	s_mov_b32 s23, 0x90000
	s_nop 0
	v_addc_co_u32_e32 v25, vcc, 0, v3, vcc
	v_add_co_u32_e32 v26, vcc, s4, v2
	s_mov_b32 s4, 0x9c000
	s_nop 0
	v_addc_co_u32_e32 v27, vcc, 0, v3, vcc
	v_add_co_u32_e32 v28, vcc, s23, v2
	s_mov_b32 s23, 0xa8000
	s_nop 0
	v_addc_co_u32_e32 v29, vcc, 0, v3, vcc
	v_add_co_u32_e32 v30, vcc, s4, v2
	v_mul_u32_u24_e32 v11, 0x41, v9
	s_nop 0
	v_addc_co_u32_e32 v31, vcc, 0, v3, vcc
	s_waitcnt lgkmcnt(0)
	v_add_co_u32_e32 v32, vcc, s23, v2
	s_mov_b32 s23, 0xb4000
	s_nop 0
	v_addc_co_u32_e32 v33, vcc, 0, v3, vcc
	v_add_co_u32_e32 v2, vcc, s23, v2
	v_lshlrev_b32_e32 v11, 2, v11
	s_nop 0
	v_addc_co_u32_e32 v3, vcc, 0, v3, vcc
	global_load_dword v19, v[20:21], off nt
	s_nop 0
	global_load_dword v20, v[22:23], off nt
	global_load_dword v21, v[24:25], off nt
	s_nop 0
	global_load_dword v22, v[26:27], off nt
	global_load_dword v23, v[28:29], off nt
	global_load_dword v24, v[30:31], off nt
	global_load_dword v25, v[32:33], off nt
	s_nop 0
	global_load_dword v26, v[2:3], off nt
	v_lshlrev_b32_e32 v27, 2, v7
	v_add3_u32 v11, s33, v11, v27
	v_mul_u32_u24_e32 v27, 0x104, v6
	v_lshl_add_u64 v[2:3], s[20:21], 0, v[0:1]
	v_lshl_add_u64 v[4:5], s[0:1], 0, v[4:5]
	v_or_b32_e32 v9, 32, v7
	v_add3_u32 v0, s33, v27, v0
	v_readlane_b32 s5, v253, 15
	v_readlane_b32 s6, v253, 16
	v_readlane_b32 s7, v253, 17
	v_readlane_b32 s8, v253, 18
	v_readlane_b32 s9, v253, 19
	v_readlane_b32 s10, v253, 20
	v_readlane_b32 s11, v253, 21
	v_readlane_b32 s14, v253, 24
	v_readlane_b32 s15, v253, 25
	v_readlane_b32 s16, v253, 26
	v_readlane_b32 s17, v253, 27
	v_readlane_b32 s18, v253, 28
	v_readlane_b32 s19, v253, 29
	s_waitcnt vmcnt(0)
	s_branch .LBB0_1039

.LBB0_1039:
	v_mov_b32_e32 v27, v196
	s_mov_b32 s0, s34
	s_waitcnt vmcnt(2)
	v_mov_b32_e32 v80, v8
	v_mov_b32_e32 v81, v10
	v_mov_b32_e32 v82, v12
	v_mov_b32_e32 v83, v13
	v_mov_b32_e32 v84, v14
	v_mov_b32_e32 v85, v15
	v_mov_b32_e32 v86, v16
	v_mov_b32_e32 v87, v17
	v_mov_b32_e32 v88, v19
	v_mov_b32_e32 v89, v20
	v_mov_b32_e32 v90, v21
	v_mov_b32_e32 v91, v22
	v_mov_b32_e32 v92, v23
	v_mov_b32_e32 v93, v24
	v_mov_b32_e32 v94, v25
	v_mov_b32_e32 v95, v26
	s_lshl_b32 s0, s0, 1
	s_add_i32 s0, s0, s22
	s_cmpk_gt_i32 s0, 0x2ff
	v_readfirstlane_b32 s0, v27
	s_cbranch_scc1 .Lcv12_nn
	s_mov_b32 s1, s34
	v_mov_b32_e32 v8, v196
	s_lshl_b32 s1, s1, 1
	s_add_i32 s1, s1, s22
	v_readfirstlane_b32 s20, v8
	s_ashr_i32 s20, s20, 8
	s_add_i32 s1, s1, s20
	s_min_i32 s1, s1, 0x2ff
	s_ashr_i32 s20, s1, 31
	s_lshr_b32 s20, s20, 28
	s_add_i32 s20, s1, s20
	s_and_b32 s21, s20, 0xfff0
	s_sub_i32 s1, s1, s21
	v_lshl_or_b32 v8, s1, 6, v6
	s_lshl_b32 s1, s20, 2
	s_and_b32 s20, s1, 0xffffffc0
	s_ashr_i32 s21, s20, 31
	v_mul_lo_u32 v14, v8, s47
	v_lshl_add_u64 v[12:13], s[20:21], 2, v[2:3]
	v_ashrrev_i32_e32 v15, 31, v14
	v_lshl_add_u64 v[20:21], v[14:15], 2, v[12:13]
	v_add_co_u32_e32 v12, vcc, s36, v20
	s_mov_b32 s1, 0x60000
	s_nop 0
	v_addc_co_u32_e32 v13, vcc, 0, v21, vcc
	v_add_co_u32_e32 v14, vcc, s35, v20
	s_nop 1
	v_addc_co_u32_e32 v15, vcc, 0, v21, vcc
	v_add_co_u32_e32 v16, vcc, s51, v20
	s_nop 1
	v_addc_co_u32_e32 v17, vcc, 0, v21, vcc
	v_add_co_u32_e32 v22, vcc, s52, v20
	s_nop 1
	v_addc_co_u32_e32 v23, vcc, 0, v21, vcc
	v_add_co_u32_e32 v24, vcc, s96, v20
	s_nop 1
	v_addc_co_u32_e32 v25, vcc, 0, v21, vcc
	v_add_co_u32_e32 v26, vcc, s46, v20
	s_nop 1
	v_addc_co_u32_e32 v27, vcc, 0, v21, vcc
	v_add_co_u32_e32 v28, vcc, s97, v20
	s_nop 1
	v_addc_co_u32_e32 v29, vcc, 0, v21, vcc
	global_load_dword v8, v[20:21], off nt
	global_load_dword v10, v[12:13], off nt
	s_nop 0
	global_load_dword v12, v[14:15], off nt
	global_load_dword v13, v[16:17], off nt
	s_nop 0
	global_load_dword v14, v[22:23], off nt
	global_load_dword v15, v[24:25], off nt
	global_load_dword v16, v[26:27], off nt
	global_load_dword v17, v[28:29], off nt
	v_add_co_u32_e32 v22, vcc, s1, v20
	s_nop 1
	v_addc_co_u32_e32 v23, vcc, 0, v21, vcc
	v_add_co_u32_e32 v24, vcc, 0x6c000, v20
	s_nop 1
	v_addc_co_u32_e32 v25, vcc, 0, v21, vcc
	v_add_co_u32_e32 v26, vcc, 0x78000, v20
	s_nop 1
	v_addc_co_u32_e32 v27, vcc, 0, v21, vcc
	v_add_co_u32_e32 v28, vcc, 0x84000, v20
	s_nop 1
	v_addc_co_u32_e32 v29, vcc, 0, v21, vcc
	v_add_co_u32_e32 v30, vcc, 0x90000, v20
	s_nop 1
	v_addc_co_u32_e32 v31, vcc, 0, v21, vcc
	v_add_co_u32_e32 v32, vcc, 0x9c000, v20
	s_nop 1
	v_addc_co_u32_e32 v33, vcc, 0, v21, vcc
	v_add_co_u32_e32 v34, vcc, 0xa8000, v20
	s_nop 1
	v_addc_co_u32_e32 v35, vcc, 0, v21, vcc
	v_add_co_u32_e32 v36, vcc, 0xb4000, v20
	s_nop 1
	v_addc_co_u32_e32 v37, vcc, 0, v21, vcc
	global_load_dword v19, v[22:23], off nt
	global_load_dword v20, v[24:25], off nt
	global_load_dword v21, v[26:27], off nt
	s_nop 0
	global_load_dword v22, v[28:29], off nt
	global_load_dword v23, v[30:31], off nt
	global_load_dword v24, v[32:33], off nt
	global_load_dword v25, v[34:35], off nt
	global_load_dword v26, v[36:37], off nt

.LBB0_1041:
	v_mov_b32_e32 v4, v196
	s_mov_b32 s0, s2
	v_mov_b32_e32 v0, v196
	s_lshl_b32 s0, s0, 1
	v_readfirstlane_b32 s1, v0
	s_ashr_i32 s1, s1, 8
	v_mov_b32_e32 v0, v196
	s_add_i32 s1, s1, s0
	s_nop 0
	v_readfirstlane_b32 s0, v0
	s_ashr_i32 s0, s0, 8
	s_sub_i32 s22, s1, s0
	s_cmpk_gt_i32 s22, 0xff
	s_cbranch_scc1 .LBB0_1025
	v_readlane_b32 s4, v253, 14
	s_lshl_b64 s[0:1], s[42:43], 1
	v_readlane_b32 s14, v253, 24
	v_readlane_b32 s15, v253, 25
	s_add_u32 s0, s14, s0
	s_addc_u32 s1, s15, s1
	s_lshl_b64 s[20:21], s[42:43], 2
	v_mov_b32_e32 v0, v196
	s_add_u32 s20, s68, s20
	s_addc_u32 s21, s69, s21
	v_readfirstlane_b32 s23, v0
	s_ashr_i32 s23, s23, 8
	s_add_i32 s23, s23, s22
	s_min_i32 s23, s23, 0xff
	s_ashr_i32 s26, s23, 31
	s_lshr_b32 s26, s26, 28
	s_add_i32 s26, s23, s26
	s_and_b32 s27, s26, 0x3fffff0
	v_bfe_u32 v6, v4, 6, 2
	s_sub_i32 s23, s23, s27
	v_lshl_or_b32 v2, s23, 6, v6
	s_lshl_b32 s23, s26, 2
	s_and_b32 s26, s23, 0xffffffc0
	s_ashr_i32 s27, s26, 31
	s_lshl_b64 s[26:27], s[26:27], 2
	s_add_u32 s26, s20, s26
	v_lshlrev_b32_e32 v0, 2, v4
	s_waitcnt vmcnt(15)
	v_or_b32_e32 v10, 4, v2
	s_waitcnt vmcnt(13)
	v_or_b32_e32 v12, 8, v2
	s_waitcnt vmcnt(12)
	v_or_b32_e32 v14, 12, v2
	s_waitcnt vmcnt(0)
	v_or_b32_e32 v16, 16, v2
	v_or_b32_e32 v22, 20, v2
	v_or_b32_e32 v24, 24, v2
	v_or_b32_e32 v26, 28, v2
	s_addc_u32 s27, s21, s27
	v_and_b32_e32 v0, 0xfc, v0
	v_ashrrev_i32_e32 v3, 31, v2
	v_ashrrev_i32_e32 v11, 31, v10
	v_ashrrev_i32_e32 v13, 31, v12
	v_ashrrev_i32_e32 v15, 31, v14
	v_ashrrev_i32_e32 v17, 31, v16
	s_waitcnt lgkmcnt(4)
	v_ashrrev_i32_e32 v23, 31, v22
	v_ashrrev_i32_e32 v25, 31, v24
	v_ashrrev_i32_e32 v27, 31, v26
	v_lshl_add_u64 v[20:21], s[26:27], 0, v[0:1]
	v_lshlrev_b64 v[8:9], 12, v[2:3]
	v_lshlrev_b64 v[10:11], 12, v[10:11]
	v_lshlrev_b64 v[12:13], 12, v[12:13]
	v_lshlrev_b64 v[14:15], 12, v[14:15]
	v_lshlrev_b64 v[16:17], 12, v[16:17]
	v_lshlrev_b64 v[22:23], 12, v[22:23]
	v_lshlrev_b64 v[24:25], 12, v[24:25]
	v_lshlrev_b64 v[26:27], 12, v[26:27]
	v_lshl_add_u64 v[8:9], v[20:21], 0, v[8:9]
	v_lshl_add_u64 v[10:11], v[20:21], 0, v[10:11]
	v_lshl_add_u64 v[12:13], v[20:21], 0, v[12:13]
	v_lshl_add_u64 v[14:15], v[20:21], 0, v[14:15]
	v_lshl_add_u64 v[16:17], v[20:21], 0, v[16:17]
	v_lshl_add_u64 v[22:23], v[20:21], 0, v[22:23]
	v_lshl_add_u64 v[24:25], v[20:21], 0, v[24:25]
	v_lshl_add_u64 v[26:27], v[20:21], 0, v[26:27]
	global_load_dword v8, v[8:9], off nt
	s_nop 0
	global_load_dword v9, v[10:11], off nt
	s_nop 0
	global_load_dword v11, v[12:13], off nt
	s_nop 0
	global_load_dword v13, v[14:15], off nt
	s_nop 0
	global_load_dword v14, v[16:17], off nt
	global_load_dword v15, v[22:23], off nt
	s_nop 0
	global_load_dword v16, v[24:25], off nt
	global_load_dword v17, v[26:27], off nt
	v_or_b32_e32 v22, 32, v2
	v_or_b32_e32 v24, 36, v2
	v_or_b32_e32 v26, 40, v2
	v_ashrrev_i32_e32 v23, 31, v22
	v_ashrrev_i32_e32 v25, 31, v24
	v_ashrrev_i32_e32 v27, 31, v26
	v_or_b32_e32 v28, 44, v2
	v_or_b32_e32 v30, 48, v2
	s_waitcnt lgkmcnt(0)
	v_or_b32_e32 v32, 52, v2
	v_or_b32_e32 v34, 56, v2
	v_or_b32_e32 v2, 60, v2
	v_lshlrev_b64 v[22:23], 12, v[22:23]
	v_lshlrev_b64 v[24:25], 12, v[24:25]
	v_lshlrev_b64 v[26:27], 12, v[26:27]
	v_ashrrev_i32_e32 v29, 31, v28
	v_ashrrev_i32_e32 v31, 31, v30
	v_ashrrev_i32_e32 v33, 31, v32
	v_ashrrev_i32_e32 v35, 31, v34
	v_ashrrev_i32_e32 v3, 31, v2
	v_lshl_add_u64 v[22:23], v[20:21], 0, v[22:23]
	v_lshl_add_u64 v[24:25], v[20:21], 0, v[24:25]
	v_lshl_add_u64 v[26:27], v[20:21], 0, v[26:27]
	v_lshlrev_b64 v[28:29], 12, v[28:29]
	v_lshlrev_b64 v[30:31], 12, v[30:31]
	v_lshlrev_b64 v[32:33], 12, v[32:33]
	v_lshlrev_b64 v[34:35], 12, v[34:35]
	v_lshlrev_b64 v[2:3], 12, v[2:3]
	v_lshl_add_u64 v[28:29], v[20:21], 0, v[28:29]
	v_lshl_add_u64 v[30:31], v[20:21], 0, v[30:31]
	v_lshl_add_u64 v[32:33], v[20:21], 0, v[32:33]
	v_lshl_add_u64 v[34:35], v[20:21], 0, v[34:35]
	v_lshl_add_u64 v[2:3], v[20:21], 0, v[2:3]
	global_load_dword v19, v[22:23], off nt
	global_load_dword v20, v[24:25], off nt
	global_load_dword v21, v[26:27], off nt
	s_nop 0
	global_load_dword v22, v[28:29], off nt
	global_load_dword v23, v[30:31], off nt
	global_load_dword v24, v[32:33], off nt
	global_load_dword v25, v[34:35], off nt
	global_load_dword v26, v[2:3], off nt
	v_bfe_u32 v7, v4, 3, 5
	v_lshlrev_b32_e32 v4, 3, v4
	v_and_b32_e32 v10, 56, v4
	v_mul_u32_u24_e32 v12, 0x41, v10
	v_lshlrev_b32_e32 v12, 2, v12
	v_lshlrev_b32_e32 v27, 2, v7
	v_lshlrev_b32_e32 v4, 1, v10
	v_mov_b32_e32 v5, v1
	v_add3_u32 v12, s33, v12, v27
	v_mul_u32_u24_e32 v27, 0x104, v6
	v_lshl_add_u64 v[2:3], s[20:21], 0, v[0:1]
	v_lshl_add_u64 v[4:5], s[0:1], 0, v[4:5]
	v_or_b32_e32 v10, 32, v7
	v_add3_u32 v0, s33, v27, v0
	v_readlane_b32 s5, v253, 15
	v_readlane_b32 s6, v253, 16
	v_readlane_b32 s7, v253, 17
	v_readlane_b32 s8, v253, 18
	v_readlane_b32 s9, v253, 19
	v_readlane_b32 s10, v253, 20
	v_readlane_b32 s11, v253, 21
	v_readlane_b32 s12, v253, 22
	v_readlane_b32 s13, v253, 23
	v_readlane_b32 s16, v253, 26
	v_readlane_b32 s17, v253, 27
	v_readlane_b32 s18, v253, 28
	v_readlane_b32 s19, v253, 29
	s_waitcnt vmcnt(0)
	s_branch .LBB0_1044

.LBB0_1058:
	v_mov_b32_e32 v4, v196
	s_mov_b32 s0, s2
	v_mov_b32_e32 v0, v196
	s_lshl_b32 s0, s0, 1
	v_readfirstlane_b32 s20, v0
	s_ashr_i32 s20, s20, 8
	v_mov_b32_e32 v0, v196
	s_add_i32 s20, s20, s0
	s_mul_hi_u32 s29, s26, 0x2c0000
	v_readfirstlane_b32 s0, v0
	s_ashr_i32 s0, s0, 8
	s_sub_i32 s27, s20, s0
	s_mul_i32 s28, s26, 0x2c0000
	s_mul_hi_u32 s1, s26, 0x580000
	s_cmpk_gt_i32 s27, 0x2bf
	s_mul_i32 s0, s26, 0x580000
	s_cbranch_scc1 .LBB0_1063
	v_readlane_b32 s4, v253, 14
	s_lshl_b64 s[20:21], s[0:1], 1
	v_readlane_b32 s16, v253, 26
	v_readlane_b32 s5, v253, 15
	v_readlane_b32 s6, v253, 16
	v_readlane_b32 s7, v253, 17
	v_readlane_b32 s8, v253, 18
	v_readlane_b32 s9, v253, 19
	v_readlane_b32 s10, v253, 20
	v_readlane_b32 s11, v253, 21
	v_readlane_b32 s12, v253, 22
	v_readlane_b32 s13, v253, 23
	v_readlane_b32 s14, v253, 24
	v_readlane_b32 s15, v253, 25
	v_readlane_b32 s17, v253, 27
	v_readlane_b32 s18, v253, 28
	v_readlane_b32 s19, v253, 29
	s_add_u32 s20, s16, s20
	s_addc_u32 s21, s17, s21
	v_readlane_b32 s4, v254, 27
	s_lshl_b64 s[22:23], s[28:29], 2
	v_readlane_b32 s16, v254, 39
	v_mov_b32_e32 v0, v196
	v_readlane_b32 s17, v254, 40
	s_add_u32 s22, s16, s22
	s_addc_u32 s23, s17, s23
	v_readfirstlane_b32 s40, v0
	s_ashr_i32 s40, s40, 8
	s_add_i32 s40, s40, s27
	s_min_i32 s40, s40, 0x2bf
	s_ashr_i32 s41, s40, 31
	s_lshr_b32 s41, s41, 28
	s_add_i32 s41, s40, s41
	s_and_b32 s42, s41, 0x3fff0
	v_bfe_u32 v6, v4, 6, 2
	s_sub_i32 s40, s40, s42
	v_lshl_or_b32 v5, s40, 6, v6
	s_lshl_b32 s40, s41, 2
	s_andn2_b32 s40, s40, 63
	s_ashr_i32 s41, s40, 31
	s_lshl_b64 s[40:41], s[40:41], 2
	s_add_u32 s40, s22, s40
	v_lshlrev_b32_e32 v0, 2, v4
	s_addc_u32 s41, s23, s41
	v_and_b32_e32 v0, 0xfc, v0
	s_waitcnt vmcnt(1)
	v_mul_lo_u32 v8, v5, s49
	v_lshl_add_u64 v[2:3], s[40:41], 0, v[0:1]
	v_ashrrev_i32_e32 v9, 31, v8
	v_lshl_add_u64 v[2:3], v[8:9], 2, v[2:3]
	v_add_co_u32_e32 v10, vcc, s43, v2
	s_mov_b32 s4, 0x63000
	s_nop 0
	v_addc_co_u32_e32 v11, vcc, 0, v3, vcc
	v_add_co_u32_e32 v12, vcc, s44, v2
	v_bfe_u32 v7, v4, 3, 5
	s_nop 0
	v_addc_co_u32_e32 v13, vcc, 0, v3, vcc
	v_add_co_u32_e32 v14, vcc, s45, v2
	v_lshlrev_b32_e32 v4, 3, v4
	s_nop 0
	v_addc_co_u32_e32 v15, vcc, 0, v3, vcc
	s_waitcnt vmcnt(0)
	v_add_co_u32_e32 v16, vcc, s47, v2
	v_mov_b32_e32 v5, v1
	s_nop 0
	v_addc_co_u32_e32 v17, vcc, 0, v3, vcc
	v_add_co_u32_e32 v20, vcc, s48, v2
	v_readlane_b32 s5, v254, 28
	s_nop 0
	v_addc_co_u32_e32 v21, vcc, 0, v3, vcc
	v_add_co_u32_e32 v22, vcc, s38, v2
	v_readlane_b32 s6, v254, 29
	s_waitcnt lgkmcnt(4)
	v_addc_co_u32_e32 v23, vcc, 0, v3, vcc
	v_add_co_u32_e32 v24, vcc, s50, v2
	v_readlane_b32 s7, v254, 30
	s_nop 0
	v_addc_co_u32_e32 v25, vcc, 0, v3, vcc
	global_load_dword v8, v[2:3], off nt
	global_load_dword v9, v[10:11], off nt
	s_nop 0
	global_load_dword v11, v[12:13], off nt
	s_nop 0
	global_load_dword v13, v[14:15], off nt
	s_nop 0
	global_load_dword v14, v[16:17], off nt
	global_load_dword v15, v[20:21], off nt
	s_nop 0
	global_load_dword v16, v[22:23], off nt
	global_load_dword v17, v[24:25], off nt
	v_add_co_u32_e32 v20, vcc, s51, v2
	v_and_b32_e32 v10, 56, v4
	s_nop 0
	v_addc_co_u32_e32 v21, vcc, 0, v3, vcc
	v_add_co_u32_e32 v22, vcc, s4, v2
	s_mov_b32 s4, 0x6e000
	s_nop 0
	v_addc_co_u32_e32 v23, vcc, 0, v3, vcc
	v_add_co_u32_e32 v24, vcc, s4, v2
	s_mov_b32 s4, 0x79000
	s_nop 0
	v_addc_co_u32_e32 v25, vcc, 0, v3, vcc
	v_add_co_u32_e32 v26, vcc, s4, v2
	s_mov_b32 s4, 0x8f000
	s_nop 0
	v_addc_co_u32_e32 v27, vcc, 0, v3, vcc
	v_add_co_u32_e32 v28, vcc, s46, v2
	v_mul_u32_u24_e32 v12, 0x41, v10
	s_nop 0
	v_addc_co_u32_e32 v29, vcc, 0, v3, vcc
	v_add_co_u32_e32 v30, vcc, s4, v2
	s_mov_b32 s4, 0x9a000
	s_nop 0
	v_addc_co_u32_e32 v31, vcc, 0, v3, vcc
	s_waitcnt lgkmcnt(0)
	v_add_co_u32_e32 v32, vcc, s4, v2
	s_mov_b32 s4, 0xa5000
	s_nop 0
	v_addc_co_u32_e32 v33, vcc, 0, v3, vcc
	v_add_co_u32_e32 v2, vcc, s4, v2
	v_lshlrev_b32_e32 v12, 2, v12
	s_nop 0
	v_addc_co_u32_e32 v3, vcc, 0, v3, vcc
	global_load_dword v19, v[20:21], off nt
	s_nop 0
	global_load_dword v20, v[22:23], off nt
	global_load_dword v21, v[24:25], off nt
	s_nop 0
	global_load_dword v22, v[26:27], off nt
	global_load_dword v23, v[28:29], off nt
	global_load_dword v24, v[30:31], off nt
	global_load_dword v25, v[32:33], off nt
	s_nop 0
	global_load_dword v26, v[2:3], off nt
	v_lshlrev_b32_e32 v27, 2, v7
	v_lshlrev_b32_e32 v4, 1, v10
	v_add3_u32 v12, s33, v12, v27
	v_mul_u32_u24_e32 v27, 0x104, v6
	v_lshl_add_u64 v[2:3], s[22:23], 0, v[0:1]
	v_lshl_add_u64 v[4:5], s[20:21], 0, v[4:5]
	v_or_b32_e32 v10, 32, v7
	v_add3_u32 v0, s33, v27, v0
	v_readlane_b32 s8, v254, 31
	v_readlane_b32 s9, v254, 32
	v_readlane_b32 s10, v254, 33
	v_readlane_b32 s11, v254, 34
	v_readlane_b32 s12, v254, 35
	v_readlane_b32 s13, v254, 36
	v_readlane_b32 s14, v254, 37
	v_readlane_b32 s15, v254, 38
	v_readlane_b32 s18, v254, 41
	v_readlane_b32 s19, v254, 42
	s_waitcnt vmcnt(0)
	s_branch .LBB0_1061

.LBB0_1061:
	v_mov_b32_e32 v27, v196
	s_mov_b32 s20, s34
	s_waitcnt vmcnt(2)
	v_mov_b32_e32 v60, v8
	v_mov_b32_e32 v61, v9
	v_mov_b32_e32 v62, v11
	v_mov_b32_e32 v63, v13
	v_mov_b32_e32 v64, v14
	v_mov_b32_e32 v65, v15
	v_mov_b32_e32 v66, v16
	v_mov_b32_e32 v67, v17
	v_mov_b32_e32 v68, v19
	v_mov_b32_e32 v69, v20
	v_mov_b32_e32 v70, v21
	v_mov_b32_e32 v71, v22
	v_mov_b32_e32 v72, v23
	v_mov_b32_e32 v73, v24
	v_mov_b32_e32 v74, v25
	v_mov_b32_e32 v75, v26
	s_lshl_b32 s20, s20, 1
	s_add_i32 s20, s20, s27
	s_cmpk_gt_i32 s20, 0x2bf
	v_readfirstlane_b32 s20, v27
	s_cbranch_scc1 .Lcv0_nn
	s_mov_b32 s21, s34
	v_mov_b32_e32 v8, v196
	s_lshl_b32 s21, s21, 1
	s_add_i32 s21, s21, s27
	v_readfirstlane_b32 s22, v8
	s_ashr_i32 s22, s22, 8
	s_add_i32 s21, s21, s22
	s_min_i32 s21, s21, 0x2bf
	s_ashr_i32 s22, s21, 31
	s_lshr_b32 s22, s22, 28
	s_add_i32 s22, s21, s22
	s_and_b32 s23, s22, 0x3fff0
	s_sub_i32 s21, s21, s23
	v_lshl_or_b32 v11, s21, 6, v6
	s_lshl_b32 s21, s22, 2
	s_and_b32 s22, s21, 0xffffffc0
	s_ashr_i32 s23, s22, 31
	v_mul_lo_u32 v14, v11, s49
	v_lshl_add_u64 v[8:9], s[22:23], 2, v[2:3]
	v_ashrrev_i32_e32 v15, 31, v14
	v_lshl_add_u64 v[20:21], v[14:15], 2, v[8:9]
	v_add_co_u32_e32 v14, vcc, s43, v20
	s_nop 1
	v_addc_co_u32_e32 v15, vcc, 0, v21, vcc
	v_add_co_u32_e32 v16, vcc, s44, v20
	s_nop 1
	v_addc_co_u32_e32 v17, vcc, 0, v21, vcc
	v_add_co_u32_e32 v22, vcc, s45, v20
	s_nop 1
	v_addc_co_u32_e32 v23, vcc, 0, v21, vcc
	v_add_co_u32_e32 v24, vcc, s47, v20
	s_nop 1
	v_addc_co_u32_e32 v25, vcc, 0, v21, vcc
	v_add_co_u32_e32 v26, vcc, s48, v20
	s_nop 1
	v_addc_co_u32_e32 v27, vcc, 0, v21, vcc
	v_add_co_u32_e32 v28, vcc, s38, v20
	s_nop 1
	v_addc_co_u32_e32 v29, vcc, 0, v21, vcc
	v_add_co_u32_e32 v30, vcc, s50, v20
	s_nop 1
	v_addc_co_u32_e32 v31, vcc, 0, v21, vcc
	global_load_dword v8, v[20:21], off nt
	global_load_dword v9, v[14:15], off nt
	global_load_dword v11, v[16:17], off nt
	global_load_dword v13, v[22:23], off nt
	s_nop 0
	global_load_dword v14, v[24:25], off nt
	global_load_dword v15, v[26:27], off nt
	global_load_dword v16, v[28:29], off nt
	global_load_dword v17, v[30:31], off nt
	v_add_co_u32_e32 v22, vcc, s51, v20
	s_nop 1
	v_addc_co_u32_e32 v23, vcc, 0, v21, vcc
	v_add_co_u32_e32 v24, vcc, 0x63000, v20
	s_nop 1
	v_addc_co_u32_e32 v25, vcc, 0, v21, vcc
	v_add_co_u32_e32 v26, vcc, 0x6e000, v20
	s_nop 1
	v_addc_co_u32_e32 v27, vcc, 0, v21, vcc
	v_add_co_u32_e32 v28, vcc, 0x79000, v20
	s_nop 1
	v_addc_co_u32_e32 v29, vcc, 0, v21, vcc
	v_add_co_u32_e32 v30, vcc, 0x84000, v20
	s_nop 1
	v_addc_co_u32_e32 v31, vcc, 0, v21, vcc
	v_add_co_u32_e32 v32, vcc, 0x8f000, v20
	s_nop 1
	v_addc_co_u32_e32 v33, vcc, 0, v21, vcc
	v_add_co_u32_e32 v34, vcc, 0x9a000, v20
	s_nop 1
	v_addc_co_u32_e32 v35, vcc, 0, v21, vcc
	v_add_co_u32_e32 v36, vcc, 0xa5000, v20
	s_nop 1
	v_addc_co_u32_e32 v37, vcc, 0, v21, vcc
	global_load_dword v19, v[22:23], off nt
	global_load_dword v20, v[24:25], off nt
	global_load_dword v21, v[26:27], off nt
	s_nop 0
	global_load_dword v22, v[28:29], off nt
	global_load_dword v23, v[30:31], off nt
	global_load_dword v24, v[32:33], off nt
	global_load_dword v25, v[34:35], off nt
	global_load_dword v26, v[36:37], off nt
.Lcv0_nn:
	ds_write_b32 v0, v60
	ds_write_b32 v0, v61 offset:1040
	ds_write_b32 v0, v62 offset:2080
	ds_write_b32 v0, v63 offset:3120
	ds_write_b32 v0, v64 offset:4160
	ds_write_b32 v0, v65 offset:5200
	ds_write_b32 v0, v66 offset:6240
	ds_write_b32 v0, v67 offset:7280
	ds_write_b32 v0, v68 offset:8320
	ds_write_b32 v0, v69 offset:9360
	ds_write_b32 v0, v70 offset:10400
	ds_write_b32 v0, v71 offset:11440
	ds_write_b32 v0, v72 offset:12480
	ds_write_b32 v0, v73 offset:13520
	ds_write_b32 v0, v74 offset:14560
	ds_write_b32 v0, v75 offset:15600
	s_waitcnt lgkmcnt(0)
	s_barrier
	s_branch .LBB0_1060
.LBB0_1063:
	v_mov_b32_e32 v4, v196
	s_mov_b32 s20, s2
	v_mov_b32_e32 v0, v196
	s_lshl_b32 s20, s20, 1
	v_readfirstlane_b32 s21, v0
	s_ashr_i32 s21, s21, 8
	v_mov_b32_e32 v0, v196
	s_add_i32 s21, s21, s20
	s_nop 0
	v_readfirstlane_b32 s20, v0
	s_ashr_i32 s20, s20, 8
	s_sub_i32 s22, s21, s20
	s_cmpk_gt_i32 s22, 0x2bf
	s_cbranch_scc1 .LBB0_1068
	v_readlane_b32 s4, v253, 14
	s_lshl_b64 s[0:1], s[0:1], 1
	v_readlane_b32 s16, v253, 26
	v_readlane_b32 s5, v253, 15
	v_readlane_b32 s6, v253, 16
	v_readlane_b32 s7, v253, 17
	v_readlane_b32 s8, v253, 18
	v_readlane_b32 s9, v253, 19
	v_readlane_b32 s10, v253, 20
	v_readlane_b32 s11, v253, 21
	v_readlane_b32 s12, v253, 22
	v_readlane_b32 s13, v253, 23
	v_readlane_b32 s14, v253, 24
	v_readlane_b32 s15, v253, 25
	v_readlane_b32 s17, v253, 27
	v_readlane_b32 s18, v253, 28
	v_readlane_b32 s19, v253, 29
	s_add_u32 s0, s16, s0
	s_addc_u32 s1, s17, s1
	v_readlane_b32 s4, v254, 27
	s_lshl_b64 s[20:21], s[28:29], 2
	v_readlane_b32 s18, v254, 41
	v_mov_b32_e32 v0, v196
	v_readlane_b32 s19, v254, 42
	s_add_u32 s20, s18, s20
	s_addc_u32 s21, s19, s21
	v_readfirstlane_b32 s23, v0
	s_ashr_i32 s23, s23, 8
	s_add_i32 s23, s23, s22
	s_min_i32 s23, s23, 0x2bf
	s_ashr_i32 s27, s23, 31
	s_lshr_b32 s27, s27, 28
	s_add_i32 s27, s23, s27
	s_and_b32 s40, s27, 0x3fff0
	v_bfe_u32 v6, v4, 6, 2
	s_sub_i32 s23, s23, s40
	v_lshl_or_b32 v5, s23, 6, v6
	s_lshl_b32 s23, s27, 2
	s_and_b32 s40, s23, 0xffffffc0
	s_ashr_i32 s41, s40, 31
	s_lshl_b64 s[40:41], s[40:41], 2
	s_add_u32 s40, s20, s40
	v_lshlrev_b32_e32 v0, 2, v4
	s_addc_u32 s41, s21, s41
	v_and_b32_e32 v0, 0xfc, v0
	s_waitcnt vmcnt(1)
	v_mul_lo_u32 v8, v5, s49
	v_lshl_add_u64 v[2:3], s[40:41], 0, v[0:1]
	v_ashrrev_i32_e32 v9, 31, v8
	v_lshl_add_u64 v[2:3], v[8:9], 2, v[2:3]
	v_add_co_u32_e32 v10, vcc, s43, v2
	s_mov_b32 s4, 0x63000
	s_nop 0
	v_addc_co_u32_e32 v11, vcc, 0, v3, vcc
	v_add_co_u32_e32 v12, vcc, s44, v2
	v_bfe_u32 v7, v4, 3, 5
	s_nop 0
	v_addc_co_u32_e32 v13, vcc, 0, v3, vcc
	v_add_co_u32_e32 v14, vcc, s45, v2
	v_lshlrev_b32_e32 v4, 3, v4
	s_nop 0
	v_addc_co_u32_e32 v15, vcc, 0, v3, vcc
	s_waitcnt vmcnt(0)
	v_add_co_u32_e32 v16, vcc, s47, v2
	v_mov_b32_e32 v5, v1
	s_nop 0
	v_addc_co_u32_e32 v17, vcc, 0, v3, vcc
	v_add_co_u32_e32 v20, vcc, s48, v2
	v_readlane_b32 s5, v254, 28
	s_nop 0
	v_addc_co_u32_e32 v21, vcc, 0, v3, vcc
	v_add_co_u32_e32 v22, vcc, s38, v2
	v_readlane_b32 s6, v254, 29
	s_waitcnt lgkmcnt(4)
	v_addc_co_u32_e32 v23, vcc, 0, v3, vcc
	v_add_co_u32_e32 v24, vcc, s50, v2
	v_readlane_b32 s7, v254, 30
	s_nop 0
	v_addc_co_u32_e32 v25, vcc, 0, v3, vcc
	global_load_dword v8, v[2:3], off nt
	global_load_dword v9, v[10:11], off nt
	s_nop 0
	global_load_dword v11, v[12:13], off nt
	s_nop 0
	global_load_dword v13, v[14:15], off nt
	s_nop 0
	global_load_dword v14, v[16:17], off nt
	global_load_dword v15, v[20:21], off nt
	s_nop 0
	global_load_dword v16, v[22:23], off nt
	global_load_dword v17, v[24:25], off nt
	v_add_co_u32_e32 v20, vcc, s51, v2
	v_and_b32_e32 v10, 56, v4
	s_nop 0
	v_addc_co_u32_e32 v21, vcc, 0, v3, vcc
	v_add_co_u32_e32 v22, vcc, s4, v2
	s_mov_b32 s4, 0x6e000
	s_nop 0
	v_addc_co_u32_e32 v23, vcc, 0, v3, vcc
	v_add_co_u32_e32 v24, vcc, s4, v2
	s_mov_b32 s4, 0x79000
	s_nop 0
	v_addc_co_u32_e32 v25, vcc, 0, v3, vcc
	v_add_co_u32_e32 v26, vcc, s4, v2
	s_mov_b32 s4, 0x8f000
	s_nop 0
	v_addc_co_u32_e32 v27, vcc, 0, v3, vcc
	v_add_co_u32_e32 v28, vcc, s46, v2
	v_mul_u32_u24_e32 v12, 0x41, v10
	s_nop 0
	v_addc_co_u32_e32 v29, vcc, 0, v3, vcc
	v_add_co_u32_e32 v30, vcc, s4, v2
	s_mov_b32 s4, 0x9a000
	s_nop 0
	v_addc_co_u32_e32 v31, vcc, 0, v3, vcc
	s_waitcnt lgkmcnt(0)
	v_add_co_u32_e32 v32, vcc, s4, v2
	s_mov_b32 s4, 0xa5000
	s_nop 0
	v_addc_co_u32_e32 v33, vcc, 0, v3, vcc
	v_add_co_u32_e32 v2, vcc, s4, v2
	v_lshlrev_b32_e32 v12, 2, v12
	s_nop 0
	v_addc_co_u32_e32 v3, vcc, 0, v3, vcc
	global_load_dword v19, v[20:21], off nt
	s_nop 0
	global_load_dword v20, v[22:23], off nt
	global_load_dword v21, v[24:25], off nt
	s_nop 0
	global_load_dword v22, v[26:27], off nt
	global_load_dword v23, v[28:29], off nt
	global_load_dword v24, v[30:31], off nt
	global_load_dword v25, v[32:33], off nt
	s_nop 0
	global_load_dword v26, v[2:3], off nt
	v_lshlrev_b32_e32 v27, 2, v7
	v_lshlrev_b32_e32 v4, 1, v10
	v_add3_u32 v12, s33, v12, v27
	v_mul_u32_u24_e32 v27, 0x104, v6
	v_lshl_add_u64 v[2:3], s[20:21], 0, v[0:1]
	v_lshl_add_u64 v[4:5], s[0:1], 0, v[4:5]
	v_or_b32_e32 v10, 32, v7
	v_add3_u32 v0, s33, v27, v0
	v_readlane_b32 s8, v254, 31
	v_readlane_b32 s9, v254, 32
	v_readlane_b32 s10, v254, 33
	v_readlane_b32 s11, v254, 34
	v_readlane_b32 s12, v254, 35
	v_readlane_b32 s13, v254, 36
	v_readlane_b32 s14, v254, 37
	v_readlane_b32 s15, v254, 38
	v_readlane_b32 s16, v254, 39
	v_readlane_b32 s17, v254, 40
	s_waitcnt vmcnt(0)
	s_branch .LBB0_1066

.LBB0_1066:
	v_mov_b32_e32 v27, v196
	s_mov_b32 s0, s34
	s_waitcnt vmcnt(2)
	v_mov_b32_e32 v60, v8
	v_mov_b32_e32 v61, v9
	v_mov_b32_e32 v62, v11
	v_mov_b32_e32 v63, v13
	v_mov_b32_e32 v64, v14
	v_mov_b32_e32 v65, v15
	v_mov_b32_e32 v66, v16
	v_mov_b32_e32 v67, v17
	v_mov_b32_e32 v68, v19
	v_mov_b32_e32 v69, v20
	v_mov_b32_e32 v70, v21
	v_mov_b32_e32 v71, v22
	v_mov_b32_e32 v72, v23
	v_mov_b32_e32 v73, v24
	v_mov_b32_e32 v74, v25
	v_mov_b32_e32 v75, v26
	s_lshl_b32 s0, s0, 1
	s_add_i32 s0, s0, s22
	s_cmpk_gt_i32 s0, 0x2bf
	v_readfirstlane_b32 s0, v27
	s_cbranch_scc1 .Lcv1_nn
	s_mov_b32 s1, s34
	v_mov_b32_e32 v8, v196
	s_lshl_b32 s1, s1, 1
	s_add_i32 s1, s1, s22
	v_readfirstlane_b32 s20, v8
	s_ashr_i32 s20, s20, 8
	s_add_i32 s1, s1, s20
	s_min_i32 s1, s1, 0x2bf
	s_ashr_i32 s20, s1, 31
	s_lshr_b32 s20, s20, 28
	s_add_i32 s20, s1, s20
	s_and_b32 s21, s20, 0x3fff0
	s_sub_i32 s1, s1, s21
	v_lshl_or_b32 v11, s1, 6, v6
	s_lshl_b32 s1, s20, 2
	s_and_b32 s20, s1, 0xffffffc0
	s_ashr_i32 s21, s20, 31
	v_mul_lo_u32 v14, v11, s49
	v_lshl_add_u64 v[8:9], s[20:21], 2, v[2:3]
	v_ashrrev_i32_e32 v15, 31, v14
	v_lshl_add_u64 v[20:21], v[14:15], 2, v[8:9]
	v_add_co_u32_e32 v14, vcc, s43, v20
	s_nop 1
	v_addc_co_u32_e32 v15, vcc, 0, v21, vcc
	v_add_co_u32_e32 v16, vcc, s44, v20
	s_nop 1
	v_addc_co_u32_e32 v17, vcc, 0, v21, vcc
	v_add_co_u32_e32 v22, vcc, s45, v20
	s_nop 1
	v_addc_co_u32_e32 v23, vcc, 0, v21, vcc
	v_add_co_u32_e32 v24, vcc, s47, v20
	s_nop 1
	v_addc_co_u32_e32 v25, vcc, 0, v21, vcc
	v_add_co_u32_e32 v26, vcc, s48, v20
	s_nop 1
	v_addc_co_u32_e32 v27, vcc, 0, v21, vcc
	v_add_co_u32_e32 v28, vcc, s38, v20
	s_nop 1
	v_addc_co_u32_e32 v29, vcc, 0, v21, vcc
	v_add_co_u32_e32 v30, vcc, s50, v20
	s_nop 1
	v_addc_co_u32_e32 v31, vcc, 0, v21, vcc
	global_load_dword v8, v[20:21], off nt
	global_load_dword v9, v[14:15], off nt
	global_load_dword v11, v[16:17], off nt
	global_load_dword v13, v[22:23], off nt
	s_nop 0
	global_load_dword v14, v[24:25], off nt
	global_load_dword v15, v[26:27], off nt
	global_load_dword v16, v[28:29], off nt
	global_load_dword v17, v[30:31], off nt
	v_add_co_u32_e32 v22, vcc, s51, v20
	s_nop 1
	v_addc_co_u32_e32 v23, vcc, 0, v21, vcc
	v_add_co_u32_e32 v24, vcc, 0x63000, v20
	s_nop 1
	v_addc_co_u32_e32 v25, vcc, 0, v21, vcc
	v_add_co_u32_e32 v26, vcc, 0x6e000, v20
	s_nop 1
	v_addc_co_u32_e32 v27, vcc, 0, v21, vcc
	v_add_co_u32_e32 v28, vcc, 0x79000, v20
	s_nop 1
	v_addc_co_u32_e32 v29, vcc, 0, v21, vcc
	v_add_co_u32_e32 v30, vcc, 0x84000, v20
	s_nop 1
	v_addc_co_u32_e32 v31, vcc, 0, v21, vcc
	v_add_co_u32_e32 v32, vcc, 0x8f000, v20
	s_nop 1
	v_addc_co_u32_e32 v33, vcc, 0, v21, vcc
	v_add_co_u32_e32 v34, vcc, 0x9a000, v20
	s_nop 1
	v_addc_co_u32_e32 v35, vcc, 0, v21, vcc
	v_add_co_u32_e32 v36, vcc, 0xa5000, v20
	s_nop 1
	v_addc_co_u32_e32 v37, vcc, 0, v21, vcc
	global_load_dword v19, v[22:23], off nt
	global_load_dword v20, v[24:25], off nt
	global_load_dword v21, v[26:27], off nt
	s_nop 0
	global_load_dword v22, v[28:29], off nt
	global_load_dword v23, v[30:31], off nt
	global_load_dword v24, v[32:33], off nt
	global_load_dword v25, v[34:35], off nt
	global_load_dword v26, v[36:37], off nt

.LBB0_1068:
	v_mov_b32_e32 v4, v196
	s_mov_b32 s0, s2
	v_mov_b32_e32 v0, v196
	s_lshl_b32 s0, s0, 1
	v_readfirstlane_b32 s1, v0
	s_ashr_i32 s1, s1, 8
	v_mov_b32_e32 v0, v196
	s_add_i32 s1, s1, s0
	s_nop 0
	v_readfirstlane_b32 s0, v0
	s_ashr_i32 s0, s0, 8
	s_sub_i32 s22, s1, s0
	s_cmpk_gt_i32 s22, 0x2bf
	s_cbranch_scc1 .LBB0_1057
	v_readlane_b32 s4, v253, 14
	s_lshl_b64 s[0:1], s[28:29], 1
	v_readlane_b32 s18, v253, 28
	v_readlane_b32 s5, v253, 15
	v_readlane_b32 s6, v253, 16
	v_readlane_b32 s7, v253, 17
	v_readlane_b32 s8, v253, 18
	v_readlane_b32 s9, v253, 19
	v_readlane_b32 s10, v253, 20
	v_readlane_b32 s11, v253, 21
	v_readlane_b32 s12, v253, 22
	v_readlane_b32 s13, v253, 23
	v_readlane_b32 s14, v253, 24
	v_readlane_b32 s15, v253, 25
	v_readlane_b32 s16, v253, 26
	v_readlane_b32 s17, v253, 27
	v_readlane_b32 s19, v253, 29
	s_add_u32 s0, s18, s0
	s_addc_u32 s1, s19, s1
	s_mul_i32 s20, s26, 0xb00000
	v_readlane_b32 s4, v254, 59
	v_mov_b32_e32 v0, v196
	s_mul_hi_u32 s21, s26, 0xb00000
	v_readlane_b32 s5, v254, 60
	s_add_u32 s20, s4, s20
	s_addc_u32 s21, s5, s21
	v_readfirstlane_b32 s23, v0
	s_ashr_i32 s23, s23, 8
	s_add_i32 s23, s23, s22
	s_min_i32 s23, s23, 0x2bf
	s_mul_hi_i32 s27, s23, 0x2e8ba2e9
	s_lshr_b32 s28, s27, 31
	s_ashr_i32 s27, s27, 3
	s_add_i32 s27, s27, s28
	s_mul_i32 s28, s27, 44
	s_sub_i32 s23, s23, s28
	s_lshl_b32 s28, s27, 6
	v_bfe_u32 v6, v4, 6, 2
	s_ashr_i32 s29, s28, 31
	v_lshl_or_b32 v2, s23, 6, v6
	s_lshl_b64 s[28:29], s[28:29], 2
	s_add_u32 s28, s20, s28
	v_lshlrev_b32_e32 v0, 2, v4
	s_waitcnt vmcnt(15)
	v_or_b32_e32 v10, 4, v2
	s_waitcnt vmcnt(13)
	v_or_b32_e32 v12, 8, v2
	s_waitcnt vmcnt(12)
	v_or_b32_e32 v14, 12, v2
	s_waitcnt vmcnt(0)
	v_or_b32_e32 v16, 16, v2
	v_or_b32_e32 v22, 20, v2
	v_or_b32_e32 v24, 24, v2
	v_or_b32_e32 v26, 28, v2
	s_addc_u32 s29, s21, s29
	v_and_b32_e32 v0, 0xfc, v0
	v_ashrrev_i32_e32 v3, 31, v2
	v_ashrrev_i32_e32 v11, 31, v10
	v_ashrrev_i32_e32 v13, 31, v12
	v_ashrrev_i32_e32 v15, 31, v14
	v_ashrrev_i32_e32 v17, 31, v16
	s_waitcnt lgkmcnt(4)
	v_ashrrev_i32_e32 v23, 31, v22
	v_ashrrev_i32_e32 v25, 31, v24
	v_ashrrev_i32_e32 v27, 31, v26
	v_lshl_add_u64 v[20:21], s[28:29], 0, v[0:1]
	v_lshlrev_b64 v[8:9], 12, v[2:3]
	v_lshlrev_b64 v[10:11], 12, v[10:11]
	v_lshlrev_b64 v[12:13], 12, v[12:13]
	v_lshlrev_b64 v[14:15], 12, v[14:15]
	v_lshlrev_b64 v[16:17], 12, v[16:17]
	v_lshlrev_b64 v[22:23], 12, v[22:23]
	v_lshlrev_b64 v[24:25], 12, v[24:25]
	v_lshlrev_b64 v[26:27], 12, v[26:27]
	v_lshl_add_u64 v[8:9], v[20:21], 0, v[8:9]
	v_lshl_add_u64 v[10:11], v[20:21], 0, v[10:11]
	v_lshl_add_u64 v[12:13], v[20:21], 0, v[12:13]
	v_lshl_add_u64 v[14:15], v[20:21], 0, v[14:15]
	v_lshl_add_u64 v[16:17], v[20:21], 0, v[16:17]
	v_lshl_add_u64 v[22:23], v[20:21], 0, v[22:23]
	v_lshl_add_u64 v[24:25], v[20:21], 0, v[24:25]
	v_lshl_add_u64 v[26:27], v[20:21], 0, v[26:27]
	global_load_dword v8, v[8:9], off nt
	s_nop 0
	global_load_dword v9, v[10:11], off nt
	s_nop 0
	global_load_dword v11, v[12:13], off nt
	s_nop 0
	global_load_dword v13, v[14:15], off nt
	s_nop 0
	global_load_dword v14, v[16:17], off nt
	global_load_dword v15, v[22:23], off nt
	s_nop 0
	global_load_dword v16, v[24:25], off nt
	global_load_dword v17, v[26:27], off nt
	v_or_b32_e32 v22, 32, v2
	v_or_b32_e32 v24, 36, v2
	v_or_b32_e32 v26, 40, v2
	v_ashrrev_i32_e32 v23, 31, v22
	v_ashrrev_i32_e32 v25, 31, v24
	v_ashrrev_i32_e32 v27, 31, v26
	v_or_b32_e32 v28, 44, v2
	v_or_b32_e32 v30, 48, v2
	s_waitcnt lgkmcnt(0)
	v_or_b32_e32 v32, 52, v2
	v_or_b32_e32 v34, 56, v2
	v_or_b32_e32 v2, 60, v2
	v_lshlrev_b64 v[22:23], 12, v[22:23]
	v_lshlrev_b64 v[24:25], 12, v[24:25]
	v_lshlrev_b64 v[26:27], 12, v[26:27]
	v_ashrrev_i32_e32 v29, 31, v28
	v_ashrrev_i32_e32 v31, 31, v30
	v_ashrrev_i32_e32 v33, 31, v32
	v_ashrrev_i32_e32 v35, 31, v34
	v_ashrrev_i32_e32 v3, 31, v2
	v_lshl_add_u64 v[22:23], v[20:21], 0, v[22:23]
	v_lshl_add_u64 v[24:25], v[20:21], 0, v[24:25]
	v_lshl_add_u64 v[26:27], v[20:21], 0, v[26:27]
	v_lshlrev_b64 v[28:29], 12, v[28:29]
	v_lshlrev_b64 v[30:31], 12, v[30:31]
	v_lshlrev_b64 v[32:33], 12, v[32:33]
	v_lshlrev_b64 v[34:35], 12, v[34:35]
	v_lshlrev_b64 v[2:3], 12, v[2:3]
	v_lshl_add_u64 v[28:29], v[20:21], 0, v[28:29]
	v_lshl_add_u64 v[30:31], v[20:21], 0, v[30:31]
	v_lshl_add_u64 v[32:33], v[20:21], 0, v[32:33]
	v_lshl_add_u64 v[34:35], v[20:21], 0, v[34:35]
	v_lshl_add_u64 v[2:3], v[20:21], 0, v[2:3]
	global_load_dword v19, v[22:23], off nt
	global_load_dword v20, v[24:25], off nt
	global_load_dword v21, v[26:27], off nt
	s_nop 0
	global_load_dword v22, v[28:29], off nt
	global_load_dword v23, v[30:31], off nt
	global_load_dword v24, v[32:33], off nt
	global_load_dword v25, v[34:35], off nt
	global_load_dword v26, v[2:3], off nt
	v_bfe_u32 v7, v4, 3, 5
	v_lshlrev_b32_e32 v4, 3, v4
	v_and_b32_e32 v10, 56, v4
	v_mul_u32_u24_e32 v12, 0x41, v10
	v_lshlrev_b32_e32 v12, 2, v12
	v_lshlrev_b32_e32 v27, 2, v7
	v_lshlrev_b32_e32 v4, 1, v10
	v_mov_b32_e32 v5, v1
	v_add3_u32 v12, s33, v12, v27
	v_mul_u32_u24_e32 v27, 0x104, v6
	v_lshl_add_u64 v[2:3], s[20:21], 0, v[0:1]
	v_lshl_add_u64 v[4:5], s[0:1], 0, v[4:5]
	v_or_b32_e32 v10, 32, v7
	v_add3_u32 v0, s33, v27, v0
	v_readlane_b32 s6, v254, 61
	v_readlane_b32 s7, v254, 62
	v_readlane_b32 s8, v254, 63
	v_readlane_b32 s9, v255, 0
	v_readlane_b32 s10, v255, 1
	v_readlane_b32 s11, v255, 2
	v_readlane_b32 s12, v255, 3
	v_readlane_b32 s13, v255, 4
	v_readlane_b32 s14, v255, 5
	v_readlane_b32 s15, v255, 6
	v_readlane_b32 s16, v255, 7
	v_readlane_b32 s17, v255, 8
	v_readlane_b32 s18, v255, 9
	v_readlane_b32 s19, v255, 10
	s_waitcnt vmcnt(0)
	s_branch .LBB0_1071

.LBB0_1071:
	v_mov_b32_e32 v27, v196
	s_mov_b32 s0, s34
	s_waitcnt vmcnt(2)
	v_mov_b32_e32 v60, v8
	v_mov_b32_e32 v61, v9
	v_mov_b32_e32 v62, v11
	v_mov_b32_e32 v63, v13
	v_mov_b32_e32 v64, v14
	v_mov_b32_e32 v65, v15
	v_mov_b32_e32 v66, v16
	v_mov_b32_e32 v67, v17
	v_mov_b32_e32 v68, v19
	v_mov_b32_e32 v69, v20
	v_mov_b32_e32 v70, v21
	v_mov_b32_e32 v71, v22
	v_mov_b32_e32 v72, v23
	v_mov_b32_e32 v73, v24
	v_mov_b32_e32 v74, v25
	v_mov_b32_e32 v75, v26
	s_lshl_b32 s0, s0, 1
	s_add_i32 s0, s0, s22
	s_cmpk_gt_i32 s0, 0x2bf
	v_readfirstlane_b32 s0, v27
	s_cbranch_scc1 .Lcv2_nn
	s_mov_b32 s1, s34
	v_mov_b32_e32 v8, v196
	s_lshl_b32 s1, s1, 1
	s_add_i32 s1, s1, s22
	v_readfirstlane_b32 s20, v8
	s_ashr_i32 s20, s20, 8
	s_add_i32 s1, s1, s20
	s_min_i32 s1, s1, 0x2bf
	s_mul_hi_i32 s20, s1, 0x2e8ba2e9
	s_lshr_b32 s21, s20, 31
	s_ashr_i32 s20, s20, 3
	s_add_i32 s20, s20, s21
	s_mul_i32 s21, s20, 44
	s_sub_i32 s1, s1, s21
	v_lshl_or_b32 v20, s1, 6, v6
	s_lshl_b32 s20, s20, 6
	v_or_b32_e32 v14, 4, v20
	v_or_b32_e32 v16, 8, v20
	v_or_b32_e32 v24, 12, v20
	v_or_b32_e32 v26, 16, v20
	s_ashr_i32 s21, s20, 31
	v_ashrrev_i32_e32 v21, 31, v20
	v_ashrrev_i32_e32 v15, 31, v14
	v_ashrrev_i32_e32 v17, 31, v16
	v_ashrrev_i32_e32 v25, 31, v24
	v_ashrrev_i32_e32 v27, 31, v26
	v_or_b32_e32 v28, 20, v20
	v_or_b32_e32 v30, 24, v20
	v_or_b32_e32 v32, 28, v20
	v_lshl_add_u64 v[22:23], s[20:21], 2, v[2:3]
	v_lshlrev_b64 v[8:9], 12, v[20:21]
	v_lshlrev_b64 v[14:15], 12, v[14:15]
	v_lshlrev_b64 v[16:17], 12, v[16:17]
	v_lshlrev_b64 v[24:25], 12, v[24:25]
	v_lshlrev_b64 v[26:27], 12, v[26:27]
	v_ashrrev_i32_e32 v29, 31, v28
	v_ashrrev_i32_e32 v31, 31, v30
	v_ashrrev_i32_e32 v33, 31, v32
	v_lshl_add_u64 v[8:9], v[22:23], 0, v[8:9]
	v_lshl_add_u64 v[14:15], v[22:23], 0, v[14:15]
	v_lshl_add_u64 v[16:17], v[22:23], 0, v[16:17]
	v_lshl_add_u64 v[24:25], v[22:23], 0, v[24:25]
	v_lshl_add_u64 v[26:27], v[22:23], 0, v[26:27]
	v_lshlrev_b64 v[28:29], 12, v[28:29]
	v_lshlrev_b64 v[30:31], 12, v[30:31]
	v_lshlrev_b64 v[32:33], 12, v[32:33]
	v_lshl_add_u64 v[28:29], v[22:23], 0, v[28:29]
	v_lshl_add_u64 v[30:31], v[22:23], 0, v[30:31]
	v_lshl_add_u64 v[32:33], v[22:23], 0, v[32:33]
	global_load_dword v8, v[8:9], off nt
	s_nop 0
	global_load_dword v9, v[14:15], off nt
	global_load_dword v11, v[16:17], off nt
	global_load_dword v13, v[24:25], off nt
	s_nop 0
	global_load_dword v14, v[26:27], off nt
	global_load_dword v15, v[28:29], off nt
	global_load_dword v16, v[30:31], off nt
	global_load_dword v17, v[32:33], off nt
	v_or_b32_e32 v24, 32, v20
	v_or_b32_e32 v26, 36, v20
	v_ashrrev_i32_e32 v25, 31, v24
	v_ashrrev_i32_e32 v27, 31, v26
	v_or_b32_e32 v28, 40, v20
	v_or_b32_e32 v30, 44, v20
	v_or_b32_e32 v32, 48, v20
	v_or_b32_e32 v34, 52, v20
	v_or_b32_e32 v36, 56, v20
	v_or_b32_e32 v20, 60, v20
	v_lshlrev_b64 v[24:25], 12, v[24:25]
	v_lshlrev_b64 v[26:27], 12, v[26:27]
	v_ashrrev_i32_e32 v29, 31, v28
	v_ashrrev_i32_e32 v31, 31, v30
	v_ashrrev_i32_e32 v33, 31, v32
	v_ashrrev_i32_e32 v35, 31, v34
	v_ashrrev_i32_e32 v37, 31, v36
	v_ashrrev_i32_e32 v21, 31, v20
	v_lshl_add_u64 v[24:25], v[22:23], 0, v[24:25]
	v_lshl_add_u64 v[26:27], v[22:23], 0, v[26:27]
	v_lshlrev_b64 v[28:29], 12, v[28:29]
	v_lshlrev_b64 v[30:31], 12, v[30:31]
	v_lshlrev_b64 v[32:33], 12, v[32:33]
	v_lshlrev_b64 v[34:35], 12, v[34:35]
	v_lshlrev_b64 v[36:37], 12, v[36:37]
	v_lshlrev_b64 v[20:21], 12, v[20:21]
	v_lshl_add_u64 v[28:29], v[22:23], 0, v[28:29]
	v_lshl_add_u64 v[30:31], v[22:23], 0, v[30:31]
	v_lshl_add_u64 v[32:33], v[22:23], 0, v[32:33]
	v_lshl_add_u64 v[34:35], v[22:23], 0, v[34:35]
	v_lshl_add_u64 v[36:37], v[22:23], 0, v[36:37]
	v_lshl_add_u64 v[42:43], v[22:23], 0, v[20:21]
	global_load_dword v19, v[24:25], off nt
	global_load_dword v20, v[26:27], off nt
	global_load_dword v21, v[28:29], off nt
	global_load_dword v22, v[30:31], off nt
	global_load_dword v23, v[32:33], off nt
	s_nop 0
	global_load_dword v24, v[34:35], off nt
	global_load_dword v25, v[36:37], off nt
	global_load_dword v26, v[42:43], off nt
